# stack17: stack16 + counted LDS waits (12 fragment reads per K-half issued together) in the ff2 context-tile ring loop
# baseline (speedup 1.0000x reference)
; #define LDSP __attribute__((address_space(3)))
; #define WAIT_V0() asm volatile("s_waitcnt vmcnt(0)" ::: "memory")
; template <int EK, int TS, int KS>
; DI void ctx_tiles(const Params& p, int l, const bf16_t* __restrict__ A, const bf16_t* __restrict__ Bt, int N, int K, ldsp_t shm) {
;     ...
;         for (int t = 0; t < nt; ++t) {
;             const int cur = t & 1;
;             if (t + 1 < nt) C_STAGE(cur ^ 1, t + 1);
;             ldsp_t sa = shm + cur * 2 * TILE_A, sb = sa + TILE_A;
; #pragma unroll
;             for (int ks = 0; ks < KS; ++ks) {
;                 bf16x8 At[MT], Bf[NT];
; #pragma unroll
;                 for (int m = 0; m < MT; ++m) At[m] = *(const LDSP bf16x8*)(sa + aoff + m * (KS * 1024) + ks * 1024);
; #pragma unroll
;                 for (int n = 0; n < NT; ++n) Bf[n] = *(const LDSP bf16x8*)(sb + boff + n * (KS * 1024) + ks * 1024);
; #pragma unroll
;                 for (int m = 0; m < MT; ++m)
; #pragma unroll
;                     for (int n = 0; n < NT; ++n) acc[m][n] = __builtin_amdgcn_mfma_f32_16x16x32_bf16(Bf[n], At[m], acc[m][n], 0, 0, 0);
;             }
;             WAIT_V0(); __syncthreads();
;         }
.LBB0_247:
	s_and_b32 s45, s5, 0x10000
	s_xor_b32 s46, s45, 0x10000
	s_add_u32 s101, s100, s46
	v_lshl_add_u64 v[34:35], v[12:13], 0, s[42:43]
	s_add_u32 m0, s101, 0x1000
	s_nop 0
	global_load_lds_dwordx4 v[34:35], off
	v_lshl_add_u64 v[34:35], v[20:21], 0, s[42:43]
	s_add_u32 m0, s101, 0x9000
	s_nop 0
	global_load_lds_dwordx4 v[34:35], off
	v_lshl_add_u64 v[34:35], v[14:15], 0, s[42:43]
	s_add_u32 m0, s101, 0x1400
	s_nop 0
	global_load_lds_dwordx4 v[34:35], off
	v_lshl_add_u64 v[34:35], v[22:23], 0, s[42:43]
	s_add_u32 m0, s101, 0x9400
	s_nop 0
	global_load_lds_dwordx4 v[34:35], off
	v_or_b32_e32 v33, s45, v30
	v_add_u32_e32 v46, v33, v32
	v_add_u32_e32 v33, v33, v31
	ds_read_b128 v[60:63], v46
	ds_read_b128 v[64:67], v46 offset:8192
	ds_read_b128 v[68:71], v33 offset:32768
	ds_read_b128 v[72:75], v46 offset:1024
	ds_read_b128 v[76:79], v46 offset:9216
	ds_read_b128 v[80:83], v33 offset:33792
	ds_read_b128 v[84:87], v46 offset:2048
	ds_read_b128 v[88:91], v46 offset:10240
	ds_read_b128 v[92:95], v33 offset:34816
	ds_read_b128 v[96:99], v46 offset:3072
	ds_read_b128 v[100:103], v46 offset:11264
	ds_read_b128 v[104:107], v33 offset:35840
	s_waitcnt lgkmcnt(9)
	v_mfma_f32_16x16x32_bf16 v[0:3], v[68:71], v[60:63], v[0:3]
	v_mfma_f32_16x16x32_bf16 v[4:7], v[68:71], v[64:67], v[4:7]
	s_waitcnt lgkmcnt(6)
	v_mfma_f32_16x16x32_bf16 v[0:3], v[80:83], v[72:75], v[0:3]
	v_mfma_f32_16x16x32_bf16 v[4:7], v[80:83], v[76:79], v[4:7]
	s_waitcnt lgkmcnt(3)
	v_mfma_f32_16x16x32_bf16 v[0:3], v[92:95], v[84:87], v[0:3]
	v_mfma_f32_16x16x32_bf16 v[4:7], v[92:95], v[88:91], v[4:7]
	s_waitcnt lgkmcnt(0)
	v_mfma_f32_16x16x32_bf16 v[0:3], v[104:107], v[96:99], v[0:3]
	v_mfma_f32_16x16x32_bf16 v[4:7], v[104:107], v[100:103], v[4:7]
	s_waitcnt vmcnt(8)
	s_barrier
	s_cmpk_eq_i32 s42, 0x1c00
	s_cbranch_scc1 .Lctxring_skip
	s_add_u32 s101, s100, s45
	s_add_u32 s46, s42, 0x200
	s_addc_u32 s47, s43, 0
	v_lshl_add_u64 v[34:35], v[8:9], 0, s[46:47]
	s_add_u32 m0, s101, 0x0
	s_nop 0
	global_load_lds_dwordx4 v[34:35], off
	v_lshl_add_u64 v[34:35], v[16:17], 0, s[46:47]
	s_add_u32 m0, s101, 0x8000
	s_nop 0
	global_load_lds_dwordx4 v[34:35], off
	v_lshl_add_u64 v[34:35], v[10:11], 0, s[46:47]
	s_add_u32 m0, s101, 0x400
	s_nop 0
	global_load_lds_dwordx4 v[34:35], off
	v_lshl_add_u64 v[34:35], v[18:19], 0, s[46:47]
	s_add_u32 m0, s101, 0x8400
	s_nop 0
	global_load_lds_dwordx4 v[34:35], off
.Lctxring_skip:
	ds_read_b128 v[60:63], v46 offset:4096
	ds_read_b128 v[64:67], v46 offset:12288
	ds_read_b128 v[68:71], v33 offset:36864
	ds_read_b128 v[72:75], v46 offset:5120
	ds_read_b128 v[76:79], v46 offset:13312
	ds_read_b128 v[80:83], v33 offset:37888
	ds_read_b128 v[84:87], v46 offset:6144
	ds_read_b128 v[88:91], v46 offset:14336
	ds_read_b128 v[92:95], v33 offset:38912
	ds_read_b128 v[96:99], v46 offset:7168
	ds_read_b128 v[100:103], v46 offset:15360
	ds_read_b128 v[104:107], v33 offset:39936
	s_waitcnt lgkmcnt(9)
	v_mfma_f32_16x16x32_bf16 v[0:3], v[68:71], v[60:63], v[0:3]
	v_mfma_f32_16x16x32_bf16 v[4:7], v[68:71], v[64:67], v[4:7]
	s_waitcnt lgkmcnt(6)
	v_mfma_f32_16x16x32_bf16 v[0:3], v[80:83], v[72:75], v[0:3]
	v_mfma_f32_16x16x32_bf16 v[4:7], v[80:83], v[76:79], v[4:7]
	s_waitcnt lgkmcnt(3)
	v_mfma_f32_16x16x32_bf16 v[0:3], v[92:95], v[84:87], v[0:3]
	v_mfma_f32_16x16x32_bf16 v[4:7], v[92:95], v[88:91], v[4:7]
	s_waitcnt lgkmcnt(0)
	v_mfma_f32_16x16x32_bf16 v[0:3], v[104:107], v[96:99], v[0:3]
	v_mfma_f32_16x16x32_bf16 v[4:7], v[104:107], v[100:103], v[4:7]
	s_add_i32 s5, s5, 0x10000
	s_add_u32 s42, s42, 0x200
	s_addc_u32 s43, s43, 0
	s_cmpk_eq_i32 s42, 0x1e00
	s_waitcnt vmcnt(8)
	s_barrier
	s_cbranch_scc0 .LBB0_247
	s_waitcnt vmcnt(0)
	s_barrier
	v_add3_u32 v29, v32, v30, s13
	v_add3_u32 v30, v31, v30, s30
	ds_read_b128 v[8:11], v29 offset:1024
	ds_read_b128 v[12:15], v30
	ds_read_b128 v[16:19], v29 offset:8192
	ds_read_b128 v[20:23], v29
	s_waitcnt lgkmcnt(1)
	v_mfma_f32_16x16x32_bf16 v[4:7], v[12:15], v[16:19], v[4:7]
	s_waitcnt lgkmcnt(0)
	v_mfma_f32_16x16x32_bf16 v[0:3], v[12:15], v[20:23], v[0:3]
	ds_read_b128 v[12:15], v29 offset:9216
	ds_read_b128 v[16:19], v30 offset:1024
	s_waitcnt lgkmcnt(0)
	v_mfma_f32_16x16x32_bf16 v[0:3], v[16:19], v[8:11], v[0:3]
	v_mfma_f32_16x16x32_bf16 v[4:7], v[16:19], v[12:15], v[4:7]
	ds_read_b128 v[8:11], v29 offset:2048
	ds_read_b128 v[12:15], v29 offset:10240
	ds_read_b128 v[16:19], v30 offset:2048
	s_waitcnt lgkmcnt(0)
	v_mfma_f32_16x16x32_bf16 v[0:3], v[16:19], v[8:11], v[0:3]
	v_mfma_f32_16x16x32_bf16 v[4:7], v[16:19], v[12:15], v[4:7]
	ds_read_b128 v[8:11], v29 offset:3072
	ds_read_b128 v[12:15], v29 offset:11264
	ds_read_b128 v[16:19], v30 offset:3072
	s_waitcnt lgkmcnt(0)
	v_mfma_f32_16x16x32_bf16 v[0:3], v[16:19], v[8:11], v[0:3]
	v_mfma_f32_16x16x32_bf16 v[4:7], v[16:19], v[12:15], v[4:7]
	ds_read_b128 v[8:11], v29 offset:4096
	ds_read_b128 v[12:15], v29 offset:12288
	ds_read_b128 v[16:19], v30 offset:4096
	s_waitcnt lgkmcnt(0)
	v_mfma_f32_16x16x32_bf16 v[0:3], v[16:19], v[8:11], v[0:3]
	v_mfma_f32_16x16x32_bf16 v[4:7], v[16:19], v[12:15], v[4:7]
	ds_read_b128 v[8:11], v29 offset:5120
	ds_read_b128 v[12:15], v29 offset:13312
	ds_read_b128 v[16:19], v30 offset:5120
	s_waitcnt lgkmcnt(0)
	v_mfma_f32_16x16x32_bf16 v[0:3], v[16:19], v[8:11], v[0:3]
	v_mfma_f32_16x16x32_bf16 v[4:7], v[16:19], v[12:15], v[4:7]
	ds_read_b128 v[8:11], v29 offset:6144
	ds_read_b128 v[12:15], v29 offset:14336
	ds_read_b128 v[16:19], v30 offset:6144
	s_waitcnt lgkmcnt(0)
	v_mfma_f32_16x16x32_bf16 v[0:3], v[16:19], v[8:11], v[0:3]
	v_mfma_f32_16x16x32_bf16 v[4:7], v[16:19], v[12:15], v[4:7]
	ds_read_b128 v[8:11], v29 offset:7168
	ds_read_b128 v[12:15], v29 offset:15360
	ds_read_b128 v[16:19], v30 offset:7168
	s_waitcnt vmcnt(0)
	s_waitcnt lgkmcnt(0)
	v_mfma_f32_16x16x32_bf16 v[0:3], v[16:19], v[8:11], v[0:3]
	v_lshrrev_b32_e32 v8, 4, v27
	v_lshrrev_b32_e32 v9, 2, v28
	v_bitop3_b32 v8, v9, v25, v8 bitop3:0x36
	v_mfma_f32_16x16x32_bf16 v[4:7], v[16:19], v[12:15], v[4:7]
	v_lshlrev_b32_e32 v9, 8, v26
	v_lshl_or_b32 v8, v8, 4, v9
	s_barrier
; template <int EK>
; DI void ctx_item(const Params& p, int l, int grow, int gcol, int slot, f32x4 s0, f32x4 s1, bool lead) {
;     ...
;         const float* gate = p.mod + ((size_t)l * 5 + 4) * 6144 + (EK == 1 ? 2 : 5) * DM + gcol;
;         float* xr = p.xc + (size_t)grow * DM + gcol;
;         const float* xs = (EK == 1 && l == 0) ? p.ctx + (size_t)grow * DM + gcol : xr;
;         const f32x4 g0 = *(const f32x4*)gate, g1 = *(const f32x4*)(gate + 4);
;         f32x4 x0 = *(const f32x4*)xs, x1 = *(const f32x4*)(xs + 4);
;         x0 += g0 * s0; x1 += g1 * s1;
;         *(f32x4*)xr = x0; *(f32x4*)(xr + 4) = x1;
;         const int ln = EK == 1 ? l : l + 1;
;         const float* gnx = (EK == 1 ? p.norm2_g : p.norm1_g) + (size_t)ln * DM + gcol;
;         const float* scn = p.mod + ((size_t)ln * 5 + 4) * 6144 + (EK == 1 ? 4 : 1) * DM + gcol;
;         const f32x4 a0 = *(const f32x4*)gnx * (1.f + *(const f32x4*)scn), a1 = *(const f32x4*)(gnx + 4) * (1.f + *(const f32x4*)(scn + 4));
;         const f32x4 y0 = x0 * a0, y1 = x1 * a1;
;         u32x4 w; w[0] = pk2(y0[0], y0[1]); w[1] = pk2(y0[2], y0[3]); w[2] = pk2(y1[0], y1[1]); w[3] = pk2(y1[2], y1[3]);
;         *(u32x4*)(p.H + (size_t)(NLAT + grow) * DM + gcol) = w;
;         float part = x0[0] * x0[0] + x0[1] * x0[1] + x0[2] * x0[2] + x0[3] * x0[3] + x1[0] * x1[0] + x1[1] * x1[1] + x1[2] * x1[2] + x1[3] * x1[3];
;         part += __shfl_xor(part, 1); part += __shfl_xor(part, 2); part += __shfl_xor(part, 4);
;         if (lead) p.ss[((size_t)(ln * 2 + (EK == 1 ? 1 : 0)) * NTOK + NLAT + grow) * 16 + slot] = part;
; template <int EK, int TS, int KS>
; DI void ctx_tiles(const Params& p, int l, const bf16_t* __restrict__ A, const bf16_t* __restrict__ Bt, int N, int K, ldsp_t shm) {
;     ...
; #pragma unroll
;         for (int m = 0; m < MT; ++m)
; #pragma unroll
;             for (int n = 0; n < NT; ++n) {
;                 const int row = wr * WM + m * 16 + fr, ch = (wc * WN + n * 16 + fq * 4) >> 2;
;                 *(LDSP f32x4*)(shm + row * (TS * 4) + ((ch ^ (row & 15)) << 4)) = acc[m][n];
;             }
;         __syncthreads();
; #pragma unroll
;         for (int it = 0; it < (TS * TS / 8) / 512; ++it) {
;             const int item = it * 512 + tid, row = item / (TS / 8), c8 = item % (TS / 8);
;             const f32x4 s0 = *(const LDSP f32x4*)(shm + row * (TS * 4) + (((2 * c8) ^ (row & 15)) << 4));
	s_nop 0
	ds_write_b128 v8, v[0:3]
	s_nop 2
	ds_write_b128 v8, v[4:7] offset:4096
	v_ashrrev_i32_e32 v0, 31, v24
	v_lshrrev_b32_e32 v0, 29, v0
	v_add_u32_e32 v0, v24, v0
	v_ashrrev_i32_e32 v1, 3, v0
	v_and_b32_e32 v0, -8, v0
	v_sub_u32_e32 v0, v24, v0
	v_lshlrev_b32_e32 v3, 1, v0
	v_and_b32_e32 v4, 15, v1
	v_bitop3_b32 v5, v3, v1, 15 bitop3:0x78
	v_bitop3_b32 v3, v3, v4, 1 bitop3:0x36
	v_lshl_add_u32 v4, s4, 6, v1
	s_lshl_b32 s4, s40, 6
	v_lshl_add_u32 v26, v0, 3, s4
	v_cmp_lt_i32_e64 s[4:5], v134, v203
	v_cmp_eq_u32_e32 vcc, 0, v0
	v_lshlrev_b32_e32 v2, 8, v1
	v_cndmask_b32_e64 v0, v202, v134, s[4:5]
	v_cmp_lt_i32_e64 s[4:5], v135, v203
	v_lshlrev_b32_e32 v34, 2, v0
	v_lshl_add_u32 v6, v5, 4, v2
	v_cndmask_b32_e64 v0, v202, v135, s[4:5]
	v_ashrrev_i32_e32 v27, 31, v26
	v_ashrrev_i32_e32 v5, 31, v4
	v_lshlrev_b32_e32 v35, 2, v0
	v_xor_b32_e32 v0, 4, v202
	v_lshlrev_b64 v[10:11], 12, v[4:5]
	v_cmp_lt_i32_e64 s[4:5], v0, v203
	v_lshlrev_b64 v[30:31], 2, v[26:27]
	v_lshl_add_u32 v7, v3, 4, v2
	v_cndmask_b32_e64 v0, v202, v0, s[4:5]
	v_lshl_add_u64 v[14:15], s[34:35], 0, v[30:31]
	v_lshl_add_u64 v[10:11], s[70:71], 0, v[10:11]
	s_waitcnt lgkmcnt(0)
	s_barrier
	v_lshlrev_b32_e32 v36, 2, v0
	ds_read_b128 v[0:3], v6
	ds_read_b128 v[6:9], v7
	v_lshl_add_u64 v[32:33], v[10:11], 0, v[30:31]
	global_load_dwordx4 v[10:13], v[14:15], off offset:16
	s_nop 0
	global_load_dwordx4 v[14:17], v[14:15], off
	s_nop 0
	global_load_dwordx4 v[18:21], v[32:33], off offset:16
	global_load_dwordx4 v[22:25], v[32:33], off
	v_lshlrev_b64 v[28:29], 11, v[4:5]
	s_waitcnt vmcnt(0) lgkmcnt(1)
	v_pk_fma_f32 v[16:17], v[2:3], v[16:17], v[24:25]
	v_pk_fma_f32 v[14:15], v[0:1], v[14:15], v[22:23]
	s_waitcnt lgkmcnt(0)
	v_pk_fma_f32 v[2:3], v[8:9], v[12:13], v[20:21]
	v_pk_fma_f32 v[0:1], v[6:7], v[10:11], v[18:19]
	global_store_dwordx4 v[32:33], v[14:17], off sc1
	global_store_dwordx4 v[32:33], v[0:3], off offset:16 sc1
	v_lshl_add_u64 v[10:11], s[36:37], 0, v[30:31]
	v_lshl_add_u64 v[22:23], s[38:39], 0, v[30:31]
	global_load_dwordx4 v[6:9], v[10:11], off offset:16
	s_nop 0
	global_load_dwordx4 v[10:13], v[10:11], off
	s_nop 0
	global_load_dwordx4 v[18:21], v[22:23], off offset:16
	s_nop 0
	global_load_dwordx4 v[22:25], v[22:23], off
	s_waitcnt vmcnt(1)
	v_pk_add_f32 v[20:21], v[20:21], 1.0 op_sel_hi:[1,0]
	s_waitcnt vmcnt(0)
	v_pk_add_f32 v[22:23], v[22:23], 1.0 op_sel_hi:[1,0]
	v_pk_add_f32 v[18:19], v[18:19], 1.0 op_sel_hi:[1,0]
	v_pk_mul_f32 v[10:11], v[10:11], v[22:23]
	v_pk_mul_f32 v[8:9], v[8:9], v[20:21]
	v_pk_mul_f32 v[6:7], v[6:7], v[18:19]
	v_pk_mul_f32 v[10:11], v[14:15], v[10:11]
	v_pk_add_f32 v[24:25], v[24:25], 1.0 op_sel_hi:[1,0]
	v_pk_mul_f32 v[18:19], v[2:3], v[8:9]
	v_pk_mul_f32 v[8:9], v[0:1], v[6:7]
	v_cvt_pk_bf16_f32 v6, v10, v11
	v_lshl_add_u64 v[10:11], s[82:83], 0, v[28:29]
	v_pk_mul_f32 v[12:13], v[12:13], v[24:25]
	v_lshl_add_u64 v[10:11], v[26:27], 1, v[10:11]
	v_pk_mul_f32 v[12:13], v[16:17], v[12:13]
	v_add_co_u32_e64 v10, s[4:5], s14, v10
	v_cvt_pk_bf16_f32 v7, v12, v13
	v_cvt_pk_bf16_f32 v8, v8, v9
	v_cvt_pk_bf16_f32 v9, v18, v19
	v_addc_co_u32_e64 v11, s[4:5], 0, v11, s[4:5]
	global_store_dwordx4 v[10:11], v[6:9], off sc1
	s_nop 1
	v_mul_f32_e32 v6, v15, v15
	v_fmac_f32_e32 v6, v14, v14
	v_fmac_f32_e32 v6, v16, v16
	v_fmac_f32_e32 v6, v17, v17
	v_fmac_f32_e32 v6, v0, v0
	v_fmac_f32_e32 v6, v1, v1
	v_fmac_f32_e32 v6, v2, v2
	v_fmac_f32_e32 v6, v3, v3
	ds_bpermute_b32 v0, v34, v6
	s_waitcnt lgkmcnt(0)
	v_add_f32_e32 v0, v6, v0
	ds_bpermute_b32 v1, v35, v0
	s_waitcnt lgkmcnt(0)
	v_add_f32_e32 v0, v0, v1
	ds_bpermute_b32 v1, v36, v0
	s_and_saveexec_b64 s[4:5], vcc
	s_cbranch_execz .LBB0_245
	v_lshl_add_u64 v[2:3], s[6:7], 0, v[4:5]
	v_lshlrev_b64 v[2:3], 6, v[2:3]
	v_lshl_add_u64 v[2:3], s[74:75], 0, v[2:3]
	v_lshl_add_u64 v[2:3], s[40:41], 2, v[2:3]
	s_waitcnt lgkmcnt(0)
	v_add_f32_e32 v0, v0, v1
	global_store_dword v[2:3], v0, off sc1
	s_branch .LBB0_245
